# v30: grid barrier pollers keep 3 staggered sc1 polls in flight (pipelined polling) in front of the serial poll loops
# speedup vs baseline: 1.0017x; 1.0017x over previous
.LBB0_26:
	s_or_b64 exec, exec, s[16:17]
	v_cvt_f32_u32_e32 v6, v4
	s_waitcnt vmcnt(0)
	v_readfirstlane_b32 s2, v5
	v_sub_u32_e32 v5, 0, v4
	v_rcp_iflag_f32_e32 v6, v6
	v_add_u32_e32 v7, s2, v3
	v_mul_f32_e32 v6, 0x4f7ffffe, v6
	v_cvt_u32_f32_e32 v6, v6
	v_mul_lo_u32 v3, v5, v6
	v_mul_hi_u32 v3, v6, v3
	v_add_u32_e32 v3, v6, v3
	v_mul_hi_u32 v3, v7, v3
	v_mul_lo_u32 v5, v3, v4
	v_sub_u32_e32 v5, v7, v5
	v_add_u32_e32 v6, 1, v3
	v_sub_u32_e32 v8, v5, v4
	v_cmp_ge_u32_e32 vcc, v5, v4
	s_nop 1
	v_cndmask_b32_e32 v3, v3, v6, vcc
	v_cndmask_b32_e32 v5, v5, v8, vcc
	v_add_u32_e32 v6, 1, v3
	v_cmp_ge_u32_e32 vcc, v5, v4
	v_add_u32_e32 v5, 1, v7
	s_nop 0
	v_cndmask_b32_e32 v3, v3, v6, vcc
	v_mul_lo_u32 v6, v4, v3
	v_add_u32_e32 v4, v6, v4
	v_cmp_ne_u32_e32 vcc, v5, v4
	s_and_saveexec_b64 s[16:17], vcc
	s_xor_b64 s[16:17], exec, s[16:17]
	s_cbranch_execz .LBB0_40
	v_readlane_b32 s18, v254, 9
	v_readlane_b32 s19, v254, 10
	s_waitcnt lgkmcnt(0)
	s_nop 3
	global_load_dword v2, v196, s[18:19] sc1
	s_waitcnt vmcnt(0)
	v_cmp_eq_u32_e32 vcc, v2, v3
	s_and_saveexec_b64 s[18:19], vcc
	s_cbranch_execz .LBB0_39
	v_readlane_b32 s42, v254, 9
	v_readlane_b32 s43, v254, 10
	s_movk_i32 s2, 0x400
	s_nop 4
	global_load_dword v5, v196, s[42:43] sc1
	s_sleep 12
	global_load_dword v6, v196, s[42:43] sc1
	s_sleep 12
.Lbq_w_loop:
	global_load_dword v7, v196, s[42:43] sc1
	s_waitcnt vmcnt(2)
	v_cmp_ne_u32_e32 vcc, v5, v3
	s_cbranch_vccnz .Lbq_w_hit
	global_load_dword v5, v196, s[42:43] sc1
	s_waitcnt vmcnt(2)
	v_cmp_ne_u32_e32 vcc, v6, v3
	s_cbranch_vccnz .Lbq_w_hit
	global_load_dword v6, v196, s[42:43] sc1
	s_waitcnt vmcnt(2)
	v_cmp_ne_u32_e32 vcc, v7, v3
	s_cbranch_vccnz .Lbq_w_hit
	s_sub_i32 s2, s2, 1
	s_cmp_lg_u32 s2, 0
	s_cbranch_scc1 .Lbq_w_loop
	s_waitcnt vmcnt(0)
	s_mov_b32 s2, 1
	s_mov_b64 s[36:37], 0
	s_branch .LBB0_30
.Lbq_w_hit:
	s_or_b64 exec, exec, s[18:19]
	s_branch .Lbq_w_inv

.Lbq_w_inv:
	buffer_inv sc1
	s_waitcnt vmcnt(0)

.LBB0_43:
	s_or_b64 exec, exec, s[18:19]
	v_cvt_f32_u32_e32 v5, v2
	s_waitcnt vmcnt(0)
	v_readfirstlane_b32 s2, v4
	v_sub_u32_e32 v4, 0, v2
	v_readlane_b32 s16, v254, 13
	v_rcp_iflag_f32_e32 v5, v5
	v_add_u32_e32 v3, s2, v3
	v_add_u32_e32 v6, 1, v3
	v_readlane_b32 s17, v254, 14
	v_mul_f32_e32 v5, 0x4f7ffffe, v5
	v_cvt_u32_f32_e32 v5, v5
	s_mov_b64 s[18:19], -1
	v_mul_lo_u32 v4, v4, v5
	v_mul_hi_u32 v4, v5, v4
	v_add_u32_e32 v4, v5, v4
	v_mul_hi_u32 v4, v3, v4
	v_mul_lo_u32 v5, v4, v2
	v_sub_u32_e32 v3, v3, v5
	v_add_u32_e32 v7, 1, v4
	v_sub_u32_e32 v5, v3, v2
	v_cmp_ge_u32_e32 vcc, v3, v2
	s_nop 1
	v_cndmask_b32_e32 v4, v4, v7, vcc
	v_cndmask_b32_e32 v3, v3, v5, vcc
	v_add_u32_e32 v5, 1, v4
	v_cmp_ge_u32_e32 vcc, v3, v2
	s_nop 1
	v_cndmask_b32_e32 v4, v4, v5, vcc
	v_mul_lo_u32 v3, v2, v4
	v_add_u32_e32 v2, v3, v2
	v_cmp_ne_u32_e32 vcc, v6, v2
	v_mov_b64_e32 v[2:3], s[16:17]
	s_and_saveexec_b64 s[16:17], vcc
	s_cbranch_execz .LBB0_55
	v_readlane_b32 s18, v254, 13
	v_readlane_b32 s19, v254, 14
	s_mov_b64 s[36:37], 0
	s_nop 3
	global_load_dword v2, v196, s[18:19] sc1
	s_waitcnt vmcnt(0)
	v_cmp_eq_u32_e32 vcc, v2, v4
	s_and_saveexec_b64 s[18:19], vcc
	s_cbranch_execz .LBB0_54
	v_readlane_b32 s42, v254, 13
	v_readlane_b32 s43, v254, 14
	s_movk_i32 s2, 0x400
	s_nop 4
	global_load_dword v5, v196, s[42:43] sc1
	s_sleep 12
	global_load_dword v6, v196, s[42:43] sc1
	s_sleep 12
.Lbq_l_loop:
	global_load_dword v7, v196, s[42:43] sc1
	s_waitcnt vmcnt(2)
	v_cmp_ne_u32_e32 vcc, v5, v4
	s_cbranch_vccnz .LBB0_54
	global_load_dword v5, v196, s[42:43] sc1
	s_waitcnt vmcnt(2)
	v_cmp_ne_u32_e32 vcc, v6, v4
	s_cbranch_vccnz .LBB0_54
	global_load_dword v6, v196, s[42:43] sc1
	s_waitcnt vmcnt(2)
	v_cmp_ne_u32_e32 vcc, v7, v4
	s_cbranch_vccnz .LBB0_54
	s_sub_i32 s2, s2, 1
	s_cmp_lg_u32 s2, 0
	s_cbranch_scc1 .Lbq_l_loop
	s_waitcnt vmcnt(0)
	s_mov_b32 s2, 1
	s_branch .LBB0_47
